# sample attention: cache-row storing path waits once for the batch loads, no per-store vmcnt ladder
# speedup vs baseline: 1.0171x; 1.0035x over previous
.LBB0_380:
	v_min_i32_e32 v0, v83, v108
	v_sub_u32_e32 v0, 0x80, v0
	v_add_u32_e32 v123, 1, v83
	v_lshl_add_u32 v6, v0, v111, v85
	v_min_i32_e32 v0, v123, v108
	v_sub_u32_e32 v0, 0x80, v0
	v_add_u32_e32 v122, 2, v83
	v_lshl_add_u32 v8, v0, v111, v85
	v_min_i32_e32 v0, v122, v108
	v_sub_u32_e32 v0, 0x80, v0
	v_add_u32_e32 v117, 3, v83
	v_lshl_add_u32 v10, v0, v111, v85
	v_min_i32_e32 v0, v117, v108
	v_ashrrev_i32_e32 v7, 31, v6
	v_sub_u32_e32 v0, 0x80, v0
	v_add_u32_e32 v116, 4, v83
	v_lshlrev_b64 v[6:7], 11, v[6:7]
	v_ashrrev_i32_e32 v9, 31, v8
	v_lshl_add_u32 v12, v0, v111, v85
	v_min_i32_e32 v0, v116, v108
	v_lshl_add_u64 v[6:7], v[92:93], 0, v[6:7]
	v_lshlrev_b64 v[8:9], 11, v[8:9]
	v_sub_u32_e32 v0, 0x80, v0
	v_add_u32_e32 v115, 5, v83
	global_load_dwordx4 v[66:69], v[6:7], off
	v_lshl_add_u64 v[8:9], v[92:93], 0, v[8:9]
	v_lshl_add_u32 v14, v0, v111, v85
	v_min_i32_e32 v0, v115, v108
	global_load_dwordx4 v[62:65], v[8:9], off
	v_sub_u32_e32 v0, 0x80, v0
	v_add_u32_e32 v114, 6, v83
	v_ashrrev_i32_e32 v11, 31, v10
	v_ashrrev_i32_e32 v13, 31, v12
	v_lshl_add_u32 v16, v0, v111, v85
	v_min_i32_e32 v0, v114, v108
	v_lshlrev_b64 v[10:11], 11, v[10:11]
	v_lshlrev_b64 v[12:13], 11, v[12:13]
	v_sub_u32_e32 v0, 0x80, v0
	v_lshl_add_u64 v[10:11], v[92:93], 0, v[10:11]
	v_lshl_add_u64 v[12:13], v[92:93], 0, v[12:13]
	v_lshl_add_u32 v18, v0, v111, v85
	global_load_dwordx4 v[58:61], v[10:11], off
	global_load_dwordx4 v[54:57], v[12:13], off
	v_ashrrev_i32_e32 v15, 31, v14
	v_ashrrev_i32_e32 v17, 31, v16
	v_ashrrev_i32_e32 v19, 31, v18
	v_lshlrev_b64 v[14:15], 11, v[14:15]
	v_lshlrev_b64 v[16:17], 11, v[16:17]
	v_lshlrev_b64 v[18:19], 11, v[18:19]
	v_lshl_add_u64 v[14:15], v[92:93], 0, v[14:15]
	v_lshl_add_u64 v[16:17], v[92:93], 0, v[16:17]
	v_lshl_add_u64 v[96:97], v[92:93], 0, v[18:19]
	global_load_dwordx4 v[50:53], v[14:15], off
	global_load_dwordx4 v[46:49], v[16:17], off
	global_load_dwordx4 v[42:45], v[96:97], off
	v_add_u32_e32 v113, 7, v83
	v_min_i32_e32 v0, v113, v108
	v_sub_u32_e32 v0, 0x80, v0
	v_lshl_add_u32 v18, v0, v111, v85
	v_ashrrev_i32_e32 v19, 31, v18
	v_lshlrev_b64 v[18:19], 11, v[18:19]
	v_lshl_add_u64 v[98:99], v[92:93], 0, v[18:19]
	global_load_dwordx4 v[38:41], v[98:99], off
	global_load_dwordx4 v[34:37], v[6:7], off offset:1024
	global_load_dwordx4 v[30:33], v[8:9], off offset:1024
	global_load_dwordx4 v[26:29], v[10:11], off offset:1024
	global_load_dwordx4 v[22:25], v[12:13], off offset:1024
	global_load_dwordx4 v[18:21], v[14:15], off offset:1024
	s_nop 0
	global_load_dwordx4 v[14:17], v[16:17], off offset:1024
	s_nop 0
	global_load_dwordx4 v[10:13], v[96:97], off offset:1024
	global_load_dwordx4 v[6:9], v[98:99], off offset:1024
	s_waitcnt vmcnt(15)
	v_pk_mul_f32 v[96:97], v[66:67], v[88:89]
	v_pk_mul_f32 v[98:99], v[68:69], v[90:91]
	v_add_f32_e32 v0, v96, v97
	v_add_f32_e32 v0, v98, v0
	s_waitcnt vmcnt(14)
	v_pk_mul_f32 v[96:97], v[62:63], v[88:89]
	v_pk_mul_f32 v[100:101], v[64:65], v[90:91]
	v_add_f32_e32 v96, v96, v97
	v_add_f32_e32 v0, v99, v0
	v_add_f32_e32 v96, v100, v96
	v_add_f32_e32 v96, v101, v96
	v_add_f32_dpp v0, v0, v0 quad_perm:[1,0,3,2] row_mask:0xf bank_mask:0xf bound_ctrl:1
	s_waitcnt vmcnt(13)
	v_pk_mul_f32 v[102:103], v[58:59], v[88:89]
	s_waitcnt vmcnt(12)
	v_pk_mul_f32 v[106:107], v[54:55], v[88:89]
	v_add_f32_dpp v0, v0, v0 quad_perm:[2,3,0,1] row_mask:0xf bank_mask:0xf bound_ctrl:1
	v_add_f32_dpp v96, v96, v96 quad_perm:[1,0,3,2] row_mask:0xf bank_mask:0xf bound_ctrl:1
	v_pk_mul_f32 v[104:105], v[60:61], v[90:91]
	v_pk_mul_f32 v[124:125], v[56:57], v[90:91]
	v_add_f32_dpp v118, v0, v0 row_half_mirror row_mask:0xf bank_mask:0xf bound_ctrl:1
	v_add_f32_dpp v0, v96, v96 quad_perm:[2,3,0,1] row_mask:0xf bank_mask:0xf bound_ctrl:1
	v_mov_b32_e32 v96, v106
	v_mov_b32_e32 v97, v102
	v_mov_b32_e32 v102, v107
	v_pk_add_f32 v[96:97], v[96:97], v[102:103]
	v_mov_b32_e32 v98, v124
	v_mov_b32_e32 v99, v104
	s_waitcnt vmcnt(11)
	v_pk_mul_f32 v[126:127], v[50:51], v[88:89]
	s_waitcnt vmcnt(10)
	v_pk_mul_f32 v[100:101], v[46:47], v[88:89]
	s_waitcnt vmcnt(9)
	v_pk_mul_f32 v[132:133], v[42:43], v[88:89]
	s_waitcnt vmcnt(8)
	v_pk_mul_f32 v[136:137], v[38:39], v[88:89]
	v_pk_add_f32 v[96:97], v[98:99], v[96:97]
	v_mov_b32_e32 v104, v125
	v_pk_mul_f32 v[128:129], v[52:53], v[90:91]
	v_pk_mul_f32 v[130:131], v[48:49], v[90:91]
	v_pk_mul_f32 v[134:135], v[44:45], v[90:91]
	v_pk_mul_f32 v[138:139], v[40:41], v[90:91]
	v_pk_add_f32 v[96:97], v[104:105], v[96:97]
	v_mov_b32_e32 v102, v100
	v_mov_b32_e32 v103, v126
	v_mov_b32_e32 v126, v101
	v_mov_b32_e32 v104, v136
	v_mov_b32_e32 v105, v132
	v_mov_b32_e32 v132, v137
	v_pk_add_f32 v[100:101], v[102:103], v[126:127]
	v_mov_b32_e32 v102, v130
	v_mov_b32_e32 v103, v128
	v_pk_add_f32 v[104:105], v[104:105], v[132:133]
	v_mov_b32_e32 v106, v138
	v_mov_b32_e32 v107, v134
	v_pk_add_f32 v[100:101], v[102:103], v[100:101]
	v_mov_b32_e32 v128, v131
	v_pk_add_f32 v[104:105], v[106:107], v[104:105]
	v_mov_b32_e32 v134, v139
	v_pk_add_f32 v[100:101], v[128:129], v[100:101]
	v_pk_add_f32 v[104:105], v[134:135], v[104:105]
	v_mov_b32_dpp v99, v97 quad_perm:[1,0,3,2] row_mask:0xf bank_mask:0xf bound_ctrl:1
	v_mov_b32_dpp v98, v96 quad_perm:[1,0,3,2] row_mask:0xf bank_mask:0xf bound_ctrl:1
	v_mov_b32_dpp v103, v101 quad_perm:[1,0,3,2] row_mask:0xf bank_mask:0xf bound_ctrl:1
	v_mov_b32_dpp v102, v100 quad_perm:[1,0,3,2] row_mask:0xf bank_mask:0xf bound_ctrl:1
	v_mov_b32_dpp v107, v105 quad_perm:[1,0,3,2] row_mask:0xf bank_mask:0xf bound_ctrl:1
	v_mov_b32_dpp v106, v104 quad_perm:[1,0,3,2] row_mask:0xf bank_mask:0xf bound_ctrl:1
	v_pk_add_f32 v[96:97], v[96:97], v[98:99]
	v_pk_add_f32 v[100:101], v[100:101], v[102:103]
	v_pk_add_f32 v[104:105], v[104:105], v[106:107]
	v_mov_b32_dpp v99, v97 quad_perm:[2,3,0,1] row_mask:0xf bank_mask:0xf bound_ctrl:1
	v_mov_b32_dpp v98, v96 quad_perm:[2,3,0,1] row_mask:0xf bank_mask:0xf bound_ctrl:1
	v_mov_b32_dpp v103, v101 quad_perm:[2,3,0,1] row_mask:0xf bank_mask:0xf bound_ctrl:1
	v_mov_b32_dpp v102, v100 quad_perm:[2,3,0,1] row_mask:0xf bank_mask:0xf bound_ctrl:1
	v_mov_b32_dpp v107, v105 quad_perm:[2,3,0,1] row_mask:0xf bank_mask:0xf bound_ctrl:1
	v_mov_b32_dpp v106, v104 quad_perm:[2,3,0,1] row_mask:0xf bank_mask:0xf bound_ctrl:1
	v_pk_add_f32 v[96:97], v[96:97], v[98:99]
	v_pk_add_f32 v[100:101], v[100:101], v[102:103]
	v_pk_add_f32 v[104:105], v[104:105], v[106:107]
	v_mov_b32_dpp v99, v97 row_half_mirror row_mask:0xf bank_mask:0xf bound_ctrl:1
	v_mov_b32_dpp v98, v96 row_half_mirror row_mask:0xf bank_mask:0xf bound_ctrl:1
	v_mov_b32_dpp v103, v101 row_half_mirror row_mask:0xf bank_mask:0xf bound_ctrl:1
	v_mov_b32_dpp v102, v100 row_half_mirror row_mask:0xf bank_mask:0xf bound_ctrl:1
	v_mov_b32_dpp v107, v105 row_half_mirror row_mask:0xf bank_mask:0xf bound_ctrl:1
	v_mov_b32_dpp v106, v104 row_half_mirror row_mask:0xf bank_mask:0xf bound_ctrl:1
	v_add_f32_dpp v120, v0, v0 row_half_mirror row_mask:0xf bank_mask:0xf bound_ctrl:1
	v_pk_add_f32 v[96:97], v[96:97], v[98:99]
	v_pk_add_f32 v[100:101], v[100:101], v[102:103]
	v_pk_add_f32 v[104:105], v[104:105], v[106:107]
	v_mov_b32_dpp v119, v118 row_mirror row_mask:0xf bank_mask:0xf bound_ctrl:1
	v_mov_b32_dpp v121, v120 row_mirror row_mask:0xf bank_mask:0xf bound_ctrl:1
	v_mov_b32_dpp v99, v97 row_mirror row_mask:0xf bank_mask:0xf bound_ctrl:1
	v_mov_b32_dpp v98, v96 row_mirror row_mask:0xf bank_mask:0xf bound_ctrl:1
	v_mov_b32_dpp v103, v101 row_mirror row_mask:0xf bank_mask:0xf bound_ctrl:1
	v_mov_b32_dpp v102, v100 row_mirror row_mask:0xf bank_mask:0xf bound_ctrl:1
	v_mov_b32_dpp v107, v105 row_mirror row_mask:0xf bank_mask:0xf bound_ctrl:1
	v_mov_b32_dpp v106, v104 row_mirror row_mask:0xf bank_mask:0xf bound_ctrl:1
	s_and_saveexec_b64 s[28:29], s[54:55]
	s_cbranch_execz .LBB0_379
	s_waitcnt vmcnt(0)
	v_add_u32_e32 v0, 7, v112
	v_lshl_add_u32 v0, v0, v111, v85
	v_cmp_lt_i32_e32 vcc, 7, v0
	s_and_saveexec_b64 s[30:31], vcc
	s_cbranch_execz .LBB0_383
	v_add_u32_e32 v0, -8, v0
	v_lshlrev_b64 v[124:125], 11, v[0:1]
	v_lshl_add_u64 v[124:125], v[94:95], 0, v[124:125]
	global_store_dwordx4 v[124:125], v[66:69], off nt
	s_nop 0
	global_store_dwordx4 v[124:125], v[34:37], off offset:1024 nt
.LBB0_383:
	s_or_b64 exec, exec, s[30:31]
	v_add_u32_e32 v0, 6, v112
	v_lshl_add_u32 v0, v0, v111, v85
	v_cmp_lt_u32_e32 vcc, v123, v73
	v_cmp_lt_i32_e64 s[48:49], 7, v0
	s_and_b64 s[14:15], vcc, s[48:49]
	s_and_saveexec_b64 s[30:31], s[14:15]
	s_cbranch_execz .LBB0_385
	v_add_u32_e32 v0, -8, v0
	v_lshlrev_b64 v[66:67], 11, v[0:1]
	v_lshl_add_u64 v[66:67], v[94:95], 0, v[66:67]
	global_store_dwordx4 v[66:67], v[62:65], off nt
	s_nop 0
	global_store_dwordx4 v[66:67], v[30:33], off offset:1024 nt
.LBB0_385:
	s_or_b64 exec, exec, s[30:31]
	v_add_u32_e32 v0, 5, v112
	v_lshl_add_u32 v0, v0, v111, v85
	v_cmp_lt_u32_e32 vcc, v122, v73
	v_cmp_lt_i32_e64 s[48:49], 7, v0
	s_and_b64 s[14:15], vcc, s[48:49]
	s_and_saveexec_b64 s[30:31], s[14:15]
	s_cbranch_execz .LBB0_387
	v_add_u32_e32 v0, -8, v0
	v_lshlrev_b64 v[62:63], 11, v[0:1]
	v_lshl_add_u64 v[62:63], v[94:95], 0, v[62:63]
	global_store_dwordx4 v[62:63], v[58:61], off nt
	s_nop 0
	global_store_dwordx4 v[62:63], v[26:29], off offset:1024 nt
.LBB0_387:
	s_or_b64 exec, exec, s[30:31]
	v_add_u32_e32 v0, 4, v112
	v_lshl_add_u32 v0, v0, v111, v85
	v_cmp_lt_u32_e32 vcc, v117, v73
	v_cmp_lt_i32_e64 s[48:49], 7, v0
	s_and_b64 s[14:15], vcc, s[48:49]
	s_and_saveexec_b64 s[30:31], s[14:15]
	s_cbranch_execz .LBB0_389
	v_add_u32_e32 v0, -8, v0
	v_lshlrev_b64 v[58:59], 11, v[0:1]
	v_lshl_add_u64 v[58:59], v[94:95], 0, v[58:59]
	global_store_dwordx4 v[58:59], v[54:57], off nt
	s_nop 0
	global_store_dwordx4 v[58:59], v[22:25], off offset:1024 nt
.LBB0_389:
	s_or_b64 exec, exec, s[30:31]
	v_add_u32_e32 v0, 3, v112
	v_lshl_add_u32 v0, v0, v111, v85
	v_cmp_lt_u32_e32 vcc, v116, v73
	v_cmp_lt_i32_e64 s[48:49], 7, v0
	s_and_b64 s[14:15], vcc, s[48:49]
	s_and_saveexec_b64 s[30:31], s[14:15]
	s_cbranch_execz .LBB0_391
	v_add_u32_e32 v0, -8, v0
	v_lshlrev_b64 v[54:55], 11, v[0:1]
	v_lshl_add_u64 v[54:55], v[94:95], 0, v[54:55]
	global_store_dwordx4 v[54:55], v[50:53], off nt
	s_nop 0
	global_store_dwordx4 v[54:55], v[18:21], off offset:1024 nt
.LBB0_391:
	s_or_b64 exec, exec, s[30:31]
	v_add_u32_e32 v0, 2, v112
	v_lshl_add_u32 v0, v0, v111, v85
	v_cmp_lt_u32_e32 vcc, v115, v73
	v_cmp_lt_i32_e64 s[48:49], 7, v0
	s_and_b64 s[14:15], vcc, s[48:49]
	s_and_saveexec_b64 s[30:31], s[14:15]
	s_cbranch_execz .LBB0_393
	v_add_u32_e32 v0, -8, v0
	v_lshlrev_b64 v[50:51], 11, v[0:1]
	v_lshl_add_u64 v[50:51], v[94:95], 0, v[50:51]
	global_store_dwordx4 v[50:51], v[46:49], off nt
	s_nop 0
	global_store_dwordx4 v[50:51], v[14:17], off offset:1024 nt
.LBB0_393:
	s_or_b64 exec, exec, s[30:31]
	v_add_u32_e32 v0, 1, v112
	v_lshl_add_u32 v0, v0, v111, v85
	v_cmp_lt_u32_e32 vcc, v114, v73
	v_cmp_lt_i32_e64 s[48:49], 7, v0
	s_and_b64 s[14:15], vcc, s[48:49]
	s_and_saveexec_b64 s[30:31], s[14:15]
	s_cbranch_execz .LBB0_395
	v_add_u32_e32 v0, -8, v0
	v_lshlrev_b64 v[46:47], 11, v[0:1]
	v_lshl_add_u64 v[46:47], v[94:95], 0, v[46:47]
	global_store_dwordx4 v[46:47], v[42:45], off nt
	s_nop 0
	global_store_dwordx4 v[46:47], v[10:13], off offset:1024 nt
.LBB0_395:
	s_or_b64 exec, exec, s[30:31]
	v_lshl_add_u32 v0, v112, v111, v85
	v_cmp_lt_u32_e32 vcc, v113, v73
	v_cmp_lt_i32_e64 s[48:49], 7, v0
	s_and_b64 s[14:15], vcc, s[48:49]
	s_and_b64 exec, exec, s[14:15]
	s_cbranch_execz .Lsm_nw1
	v_add_u32_e32 v0, -8, v0
	v_lshlrev_b64 v[42:43], 11, v[0:1]
	v_lshl_add_u64 v[42:43], v[94:95], 0, v[42:43]
	global_store_dwordx4 v[42:43], v[38:41], off nt
	s_nop 0
	global_store_dwordx4 v[42:43], v[6:9], off offset:1024 nt
.Lsm_nw1:
	s_or_b64 exec, exec, s[28:29]
	v_add3_u32 v0, v73, v112, s78
	v_add_f32_e32 v38, v120, v121
	v_cmp_lt_i32_e32 vcc, 1, v0
	v_add_f32_e32 v40, v118, v119
	v_add_u32_e32 v83, 8, v83
	v_cndmask_b32_e32 v41, v193, v38, vcc
	v_pk_add_f32 v[38:39], v[96:97], v[98:99]
	v_cmp_lt_i32_e32 vcc, 3, v0
	v_max3_f32 v42, v109, v40, v41
	v_add_u32_e32 v112, -8, v112
	v_cndmask_b32_e32 v43, v193, v38, vcc
	v_cmp_lt_i32_e32 vcc, 2, v0
	s_nop 1
	v_cndmask_b32_e32 v44, v193, v39, vcc
	v_pk_add_f32 v[38:39], v[100:101], v[102:103]
	v_cmp_lt_i32_e32 vcc, 5, v0
	v_max3_f32 v42, v42, v44, v43
	s_nop 0
	v_cndmask_b32_e32 v45, v193, v38, vcc
	v_cmp_lt_i32_e32 vcc, 4, v0
	s_nop 1
	v_cndmask_b32_e32 v46, v193, v39, vcc
	v_pk_add_f32 v[38:39], v[104:105], v[106:107]
	v_cmp_lt_i32_e32 vcc, 7, v0
	v_max3_f32 v42, v42, v46, v45
	s_nop 0
	v_cndmask_b32_e32 v47, v193, v38, vcc
	v_cmp_lt_i32_e32 vcc, 6, v0
	s_nop 1
	v_cndmask_b32_e32 v39, v193, v39, vcc
	v_max3_f32 v0, v42, v39, v47
	v_sub_f32_e32 v42, v40, v0
	v_mul_f32_e32 v42, 0x3fb8aa3b, v42
	v_exp_f32_e32 v42, v42
	v_cmp_lt_f32_e32 vcc, s89, v40
	v_sub_f32_e32 v38, v109, v0
	v_mul_f32_e32 v38, 0x3fb8aa3b, v38
	v_cndmask_b32_e32 v40, 0, v42, vcc
	v_mov_b32_e32 v42, v40
	s_nop 0
	v_pk_mul_f32 v[36:37], v[36:37], v[40:41] op_sel_hi:[1,0]
	v_pk_mul_f32 v[34:35], v[34:35], v[40:41] op_sel_hi:[1,0]
	v_sub_f32_e32 v40, v41, v0
	v_mul_f32_e32 v40, 0x3fb8aa3b, v40
	v_exp_f32_e32 v38, v38
	v_exp_f32_e32 v40, v40
	v_cmp_lt_f32_e32 vcc, s89, v41
	v_mov_b32_e32 v109, v0
	v_fmac_f32_e32 v42, v110, v38
	v_pk_fma_f32 v[2:3], v[2:3], v[38:39], v[34:35] op_sel_hi:[1,0,1]
	v_pk_fma_f32 v[4:5], v[4:5], v[38:39], v[36:37] op_sel_hi:[1,0,1]
	v_cndmask_b32_e32 v34, 0, v40, vcc
	v_sub_f32_e32 v36, v44, v0
	v_add_f32_e32 v35, v34, v42
	v_mul_f32_e32 v36, 0x3fb8aa3b, v36
	v_exp_f32_e32 v36, v36
	s_nop 0
	v_pk_fma_f32 v[4:5], v[32:33], v[34:35], v[4:5] op_sel_hi:[1,0,1]
	v_sub_f32_e32 v32, v43, v0
	v_mul_f32_e32 v32, 0x3fb8aa3b, v32
	v_exp_f32_e32 v32, v32
	v_cmp_lt_f32_e32 vcc, s89, v44
	v_pk_fma_f32 v[2:3], v[30:31], v[34:35], v[2:3] op_sel_hi:[1,0,1]
	s_nop 0
	v_cndmask_b32_e32 v30, 0, v36, vcc
	v_add_f32_e32 v31, v30, v35
	v_cmp_lt_f32_e32 vcc, s89, v43
	s_nop 0
	v_pk_fma_f32 v[2:3], v[26:27], v[30:31], v[2:3] op_sel_hi:[1,0,1]
	v_pk_fma_f32 v[4:5], v[28:29], v[30:31], v[4:5] op_sel_hi:[1,0,1]
	v_cndmask_b32_e32 v26, 0, v32, vcc
	v_sub_f32_e32 v28, v46, v0
	v_add_f32_e32 v27, v26, v31
	v_mul_f32_e32 v28, 0x3fb8aa3b, v28
	v_exp_f32_e32 v28, v28
	s_nop 0
	v_pk_fma_f32 v[4:5], v[24:25], v[26:27], v[4:5] op_sel_hi:[1,0,1]
	v_sub_f32_e32 v24, v45, v0
	v_mul_f32_e32 v24, 0x3fb8aa3b, v24
	v_exp_f32_e32 v24, v24
	v_cmp_lt_f32_e32 vcc, s89, v46
	v_pk_fma_f32 v[2:3], v[22:23], v[26:27], v[2:3] op_sel_hi:[1,0,1]
	s_nop 0
	v_cndmask_b32_e32 v22, 0, v28, vcc
	v_add_f32_e32 v23, v22, v27
	v_cmp_lt_f32_e32 vcc, s89, v45
	s_nop 0
	v_pk_fma_f32 v[2:3], v[18:19], v[22:23], v[2:3] op_sel_hi:[1,0,1]
	v_pk_fma_f32 v[4:5], v[20:21], v[22:23], v[4:5] op_sel_hi:[1,0,1]
	v_cndmask_b32_e32 v18, 0, v24, vcc
	v_sub_f32_e32 v20, v39, v0
	v_add_f32_e32 v19, v18, v23
	v_mul_f32_e32 v20, 0x3fb8aa3b, v20
	v_exp_f32_e32 v20, v20
	s_nop 0
	v_pk_fma_f32 v[4:5], v[16:17], v[18:19], v[4:5] op_sel_hi:[1,0,1]
	v_sub_f32_e32 v16, v47, v0
	v_mul_f32_e32 v16, 0x3fb8aa3b, v16
	v_exp_f32_e32 v16, v16
	v_cmp_lt_f32_e32 vcc, s89, v39
	v_pk_fma_f32 v[2:3], v[14:15], v[18:19], v[2:3] op_sel_hi:[1,0,1]
	s_nop 0
	v_cndmask_b32_e32 v14, 0, v20, vcc
	v_add_f32_e32 v15, v14, v19
	v_cmp_lt_f32_e32 vcc, s89, v47
	s_nop 0
	v_pk_fma_f32 v[2:3], v[10:11], v[14:15], v[2:3] op_sel_hi:[1,0,1]
	v_pk_fma_f32 v[4:5], v[12:13], v[14:15], v[4:5] op_sel_hi:[1,0,1]
	v_cndmask_b32_e32 v10, 0, v16, vcc
	v_cmp_ge_u32_e32 vcc, v83, v73
	v_add_f32_e32 v110, v10, v15
	s_nop 0
	v_pk_fma_f32 v[4:5], v[8:9], v[10:11], v[4:5] op_sel_hi:[1,0,1]
	v_pk_fma_f32 v[2:3], v[6:7], v[10:11], v[2:3] op_sel_hi:[1,0,1]
	s_or_b64 s[26:27], vcc, s[26:27]
	s_andn2_b64 exec, exec, s[26:27]
	s_cbranch_execz .LBB0_397
	s_branch .LBB0_380
